# EpiResidNorm (3 instances): residual-stream tile loads de-serialized, ten in flight into free VGPRs, counted vmcnt waits
# speedup vs baseline: 1.0085x; 1.0011x over previous
.LBB0_530:
	s_lshl_b32 s39, s36, 8
	v_mbcnt_lo_u32_b32 v180, -1, 0
	v_mbcnt_hi_u32_b32 v180, -1, v180
	s_add_i32 s4, s39, s64
	v_and_b32_e32 v178, 15, v180
	s_lshl_b32 s5, s10, 8
	v_readlane_b32 s8, v254, 25
	v_ashrrev_i32_e32 v104, 1, v180
	s_or_b32 s5, s5, s8
	v_and_b32_e32 v104, -8, v104
	v_or_b32_e32 v148, s4, v178
	v_add_u32_e32 v144, s5, v104
	v_ashrrev_i32_e32 v149, 31, v148
	v_ashrrev_i32_e32 v145, 31, v144
	v_lshlrev_b64 v[104:105], 12, v[148:149]
	v_lshl_add_u64 v[104:105], s[20:21], 0, v[104:105]
	v_lshlrev_b64 v[150:151], 1, v[144:145]
	v_lshl_add_u64 v[146:147], v[104:105], 0, v[150:151]
	global_load_dwordx4 v[152:155], v[146:147], off
	v_lshl_add_u64 v[108:109], v[144:145], 2, s[22:23]
	global_load_dwordx4 v[136:139], v[108:109], off
	global_load_dwordx4 v[132:135], v[108:109], off offset:16
	global_load_dwordx4 v[104:107], v[108:109], off offset:528
	s_nop 0
	global_load_dwordx4 v[108:111], v[108:109], off offset:512
	s_mov_b64 s[4:5], 0x80000
	s_mov_b64 s[98:99], 0x10000
	v_lshl_add_u64 v[244:245], v[146:147], 0, s[98:99]
	s_mov_b64 s[98:99], 0x20000
	v_lshl_add_u64 v[246:247], v[146:147], 0, s[98:99]
	s_mov_b64 s[98:99], 0x30000
	v_lshl_add_u64 v[248:249], v[146:147], 0, s[98:99]
	s_mov_b64 s[98:99], 0x80000
	v_lshl_add_u64 v[250:251], v[146:147], 0, s[98:99]
	s_mov_b64 s[98:99], 0x90000
	v_lshl_add_u64 v[252:253], v[146:147], 0, s[98:99]
	s_mov_b64 s[98:99], 0xa0000
	v_lshl_add_u64 v[194:195], v[146:147], 0, s[98:99]
	s_mov_b64 s[98:99], 0xb0000
	v_lshl_add_u64 v[212:213], v[146:147], 0, s[98:99]
	global_load_dwordx4 v[186:189], v[146:147], off offset:256
	global_load_dwordx4 v[190:193], v[244:245], off
	global_load_dwordx4 v[200:203], v[244:245], off offset:256
	global_load_dwordx4 v[204:207], v[246:247], off
	global_load_dwordx4 v[208:211], v[246:247], off offset:256
	global_load_dwordx4 v[224:227], v[248:249], off
	global_load_dwordx4 v[228:231], v[248:249], off offset:256
	global_load_dwordx4 v[232:235], v[250:251], off
	global_load_dwordx4 v[236:239], v[250:251], off offset:256
	global_load_dwordx4 v[240:243], v[252:253], off
	s_waitcnt vmcnt(14)
	v_lshlrev_b32_e32 v156, 16, v152
	v_and_b32_e32 v157, 0xffff0000, v152
	v_lshlrev_b32_e32 v152, 16, v153
	v_and_b32_e32 v153, 0xffff0000, v153
	v_lshlrev_b32_e32 v158, 16, v154
	v_and_b32_e32 v159, 0xffff0000, v154
	v_lshlrev_b32_e32 v154, 16, v155
	v_and_b32_e32 v155, 0xffff0000, v155
	s_waitcnt vmcnt(13)
	v_pk_fma_f32 v[142:143], v[142:143], v[138:139], v[152:153]
	v_pk_fma_f32 v[140:141], v[140:141], v[136:137], v[156:157]
	s_waitcnt vmcnt(12)
	v_pk_fma_f32 v[152:153], v[130:131], v[134:135], v[154:155]
	v_pk_fma_f32 v[130:131], v[128:129], v[132:133], v[158:159]
	v_cvt_pk_bf16_f32 v128, v140, v141
	v_cvt_pk_bf16_f32 v129, v142, v143
	s_nop 0
	v_cvt_pk_bf16_f32 v130, v130, v131
	v_cvt_pk_bf16_f32 v131, v152, v153
	v_or_b32_e32 v152, 16, v148
	v_ashrrev_i32_e32 v153, 31, v152
	v_lshlrev_b64 v[152:153], 12, v[152:153]
	v_lshl_add_u64 v[152:153], s[20:21], 0, v[152:153]
	v_lshl_add_u64 v[152:153], v[152:153], 0, v[150:151]
	global_store_dwordx4 v[146:147], v[128:131], off
	v_and_b32_e32 v177, 0xffff0000, v128
	v_and_b32_e32 v175, 0xffff0000, v129
	v_lshlrev_b32_e32 v176, 16, v128
	v_lshlrev_b32_e32 v174, 16, v129
	v_and_b32_e32 v173, 0xffff0000, v130
	v_lshlrev_b32_e32 v172, 16, v130
	v_and_b32_e32 v171, 0xffff0000, v131
	v_lshlrev_b32_e32 v170, 16, v131
	s_waitcnt vmcnt(10)
	v_lshlrev_b32_e32 v154, 16, v186
	v_and_b32_e32 v155, 0xffff0000, v186
	v_lshlrev_b32_e32 v140, 16, v187
	v_and_b32_e32 v141, 0xffff0000, v187
	v_lshlrev_b32_e32 v156, 16, v188
	v_and_b32_e32 v157, 0xffff0000, v188
	v_lshlrev_b32_e32 v142, 16, v189
	v_and_b32_e32 v143, 0xffff0000, v189
	global_load_dwordx4 v[186:189], v[252:253], off offset:256
	v_pk_fma_f32 v[122:123], v[122:123], v[110:111], v[140:141]
	v_pk_fma_f32 v[120:121], v[120:121], v[108:109], v[154:155]
	v_pk_fma_f32 v[140:141], v[118:119], v[106:107], v[142:143]
	v_pk_fma_f32 v[118:119], v[116:117], v[104:105], v[156:157]
	v_cvt_pk_bf16_f32 v116, v120, v121
	v_cvt_pk_bf16_f32 v117, v122, v123
	s_nop 0
	v_cvt_pk_bf16_f32 v118, v118, v119
	v_cvt_pk_bf16_f32 v119, v140, v141
	v_and_b32_e32 v169, 0xffff0000, v116
	global_store_dwordx4 v[146:147], v[116:119], off offset:256
	v_and_b32_e32 v167, 0xffff0000, v117
	v_lshlrev_b32_e32 v168, 16, v116
	v_lshlrev_b32_e32 v166, 16, v117
	v_and_b32_e32 v165, 0xffff0000, v118
	v_lshlrev_b32_e32 v164, 16, v118
	v_and_b32_e32 v163, 0xffff0000, v119
	v_lshlrev_b32_e32 v162, 16, v119
	s_waitcnt vmcnt(11)
	v_lshlrev_b32_e32 v140, 16, v190
	v_and_b32_e32 v141, 0xffff0000, v190
	v_lshlrev_b32_e32 v120, 16, v191
	v_and_b32_e32 v121, 0xffff0000, v191
	v_lshlrev_b32_e32 v142, 16, v192
	v_and_b32_e32 v143, 0xffff0000, v192
	v_lshlrev_b32_e32 v122, 16, v193
	v_and_b32_e32 v123, 0xffff0000, v193
	global_load_dwordx4 v[190:193], v[194:195], off
	v_pk_fma_f32 v[120:121], v[126:127], v[138:139], v[120:121]
	v_pk_fma_f32 v[122:123], v[114:115], v[134:135], v[122:123]
	v_pk_fma_f32 v[114:115], v[112:113], v[132:133], v[142:143]
	v_pk_fma_f32 v[124:125], v[124:125], v[136:137], v[140:141]
	s_nop 0
	v_cvt_pk_bf16_f32 v112, v124, v125
	v_cvt_pk_bf16_f32 v113, v120, v121
	v_cvt_pk_bf16_f32 v114, v114, v115
	v_cvt_pk_bf16_f32 v115, v122, v123
	v_or_b32_e32 v124, 32, v148
	v_ashrrev_i32_e32 v125, 31, v124
	v_lshlrev_b64 v[124:125], 12, v[124:125]
	v_lshl_add_u64 v[124:125], s[20:21], 0, v[124:125]
	global_store_dwordx4 v[152:153], v[112:115], off
	v_lshl_add_u64 v[124:125], v[124:125], 0, v[150:151]
	s_waitcnt vmcnt(12)
	v_lshlrev_b32_e32 v126, 16, v200
	v_and_b32_e32 v127, 0xffff0000, v200
	v_lshlrev_b32_e32 v120, 16, v201
	v_and_b32_e32 v121, 0xffff0000, v201
	v_lshlrev_b32_e32 v140, 16, v202
	v_and_b32_e32 v141, 0xffff0000, v202
	v_lshlrev_b32_e32 v122, 16, v203
	v_and_b32_e32 v123, 0xffff0000, v203
	global_load_dwordx4 v[200:203], v[194:195], off offset:256
	v_pk_fma_f32 v[102:103], v[102:103], v[110:111], v[120:121]
	v_pk_fma_f32 v[120:121], v[94:95], v[106:107], v[122:123]
	v_pk_fma_f32 v[94:95], v[92:93], v[104:105], v[140:141]
	v_pk_fma_f32 v[100:101], v[100:101], v[108:109], v[126:127]
	s_nop 0
	v_cvt_pk_bf16_f32 v92, v100, v101
	v_cvt_pk_bf16_f32 v93, v102, v103
	v_cvt_pk_bf16_f32 v94, v94, v95
	v_cvt_pk_bf16_f32 v95, v120, v121
	global_store_dwordx4 v[152:153], v[92:95], off offset:256
	s_waitcnt vmcnt(13)
	v_lshlrev_b32_e32 v120, 16, v204
	v_and_b32_e32 v121, 0xffff0000, v204
	v_lshlrev_b32_e32 v100, 16, v205
	v_and_b32_e32 v101, 0xffff0000, v205
	v_lshlrev_b32_e32 v122, 16, v206
	v_and_b32_e32 v123, 0xffff0000, v206
	v_lshlrev_b32_e32 v102, 16, v207
	v_and_b32_e32 v103, 0xffff0000, v207
	global_load_dwordx4 v[204:207], v[212:213], off
	v_pk_fma_f32 v[98:99], v[98:99], v[138:139], v[100:101]
	v_pk_fma_f32 v[96:97], v[96:97], v[136:137], v[120:121]
	v_pk_fma_f32 v[100:101], v[90:91], v[134:135], v[102:103]
	v_pk_fma_f32 v[90:91], v[88:89], v[132:133], v[122:123]
	v_cvt_pk_bf16_f32 v88, v96, v97
	v_cvt_pk_bf16_f32 v89, v98, v99
	s_nop 0
	v_cvt_pk_bf16_f32 v90, v90, v91
	v_cvt_pk_bf16_f32 v91, v100, v101
	v_or_b32_e32 v100, 48, v148
	v_ashrrev_i32_e32 v101, 31, v100
	v_lshlrev_b64 v[100:101], 12, v[100:101]
	v_lshl_add_u64 v[100:101], s[20:21], 0, v[100:101]
	v_lshl_add_u64 v[100:101], v[100:101], 0, v[150:151]
	global_store_dwordx4 v[124:125], v[88:91], off
	s_waitcnt vmcnt(14)
	v_lshlrev_b32_e32 v102, 16, v208
	v_and_b32_e32 v103, 0xffff0000, v208
	v_lshlrev_b32_e32 v96, 16, v209
	v_and_b32_e32 v97, 0xffff0000, v209
	v_lshlrev_b32_e32 v120, 16, v210
	v_and_b32_e32 v121, 0xffff0000, v210
	v_lshlrev_b32_e32 v98, 16, v211
	v_and_b32_e32 v99, 0xffff0000, v211
	global_load_dwordx4 v[208:211], v[212:213], off offset:256
	v_pk_fma_f32 v[82:83], v[82:83], v[110:111], v[96:97]
	v_pk_fma_f32 v[80:81], v[80:81], v[108:109], v[102:103]
	v_pk_fma_f32 v[96:97], v[78:79], v[106:107], v[98:99]
	v_pk_fma_f32 v[78:79], v[76:77], v[104:105], v[120:121]
	v_cvt_pk_bf16_f32 v76, v80, v81
	v_cvt_pk_bf16_f32 v77, v82, v83
	s_nop 0
	v_cvt_pk_bf16_f32 v78, v78, v79
	v_cvt_pk_bf16_f32 v79, v96, v97
	s_waitcnt vmcnt(14)
	v_lshlrev_b32_e32 v96, 16, v224
	v_and_b32_e32 v97, 0xffff0000, v224
	v_lshlrev_b32_e32 v80, 16, v225
	v_and_b32_e32 v81, 0xffff0000, v225
	v_lshlrev_b32_e32 v98, 16, v226
	v_and_b32_e32 v99, 0xffff0000, v226
	v_lshlrev_b32_e32 v82, 16, v227
	v_and_b32_e32 v83, 0xffff0000, v227
	v_pk_fma_f32 v[80:81], v[86:87], v[138:139], v[80:81]
	v_pk_fma_f32 v[82:83], v[74:75], v[134:135], v[82:83]
	v_pk_fma_f32 v[74:75], v[72:73], v[132:133], v[98:99]
	global_store_dwordx4 v[124:125], v[76:79], off offset:256
	v_pk_fma_f32 v[84:85], v[84:85], v[136:137], v[96:97]
	s_nop 0
	v_cvt_pk_bf16_f32 v72, v84, v85
	v_cvt_pk_bf16_f32 v73, v80, v81
	v_cvt_pk_bf16_f32 v74, v74, v75
	v_cvt_pk_bf16_f32 v75, v82, v83
	v_add_co_u32_e32 v84, vcc, s90, v146
	global_store_dwordx4 v[100:101], v[72:75], off
	s_nop 0
	v_addc_co_u32_e32 v85, vcc, 0, v147, vcc
	s_waitcnt vmcnt(15)
	v_lshlrev_b32_e32 v86, 16, v228
	v_and_b32_e32 v87, 0xffff0000, v228
	v_lshlrev_b32_e32 v80, 16, v229
	v_and_b32_e32 v81, 0xffff0000, v229
	v_lshlrev_b32_e32 v96, 16, v230
	v_and_b32_e32 v97, 0xffff0000, v230
	v_lshlrev_b32_e32 v82, 16, v231
	v_and_b32_e32 v83, 0xffff0000, v231
	v_pk_fma_f32 v[70:71], v[70:71], v[110:111], v[80:81]
	v_pk_fma_f32 v[80:81], v[66:67], v[106:107], v[82:83]
	v_pk_fma_f32 v[66:67], v[64:65], v[104:105], v[96:97]
	v_pk_fma_f32 v[68:69], v[68:69], v[108:109], v[86:87]
	s_nop 0
	v_cvt_pk_bf16_f32 v64, v68, v69
	v_cvt_pk_bf16_f32 v65, v70, v71
	v_cvt_pk_bf16_f32 v66, v66, v67
	v_cvt_pk_bf16_f32 v67, v80, v81
	global_store_dwordx4 v[100:101], v[64:67], off offset:256
	v_lshl_add_u64 v[80:81], v[146:147], 0, s[4:5]
	s_mov_b64 s[4:5], 0x90000
	s_waitcnt vmcnt(15)
	v_lshlrev_b32_e32 v82, 16, v232
	v_and_b32_e32 v83, 0xffff0000, v232
	v_lshlrev_b32_e32 v68, 16, v233
	v_and_b32_e32 v69, 0xffff0000, v233
	v_lshlrev_b32_e32 v86, 16, v234
	v_and_b32_e32 v87, 0xffff0000, v234
	v_lshlrev_b32_e32 v70, 16, v235
	v_and_b32_e32 v71, 0xffff0000, v235
	v_pk_fma_f32 v[62:63], v[62:63], v[138:139], v[68:69]
	v_pk_fma_f32 v[60:61], v[60:61], v[136:137], v[82:83]
	v_pk_fma_f32 v[68:69], v[58:59], v[134:135], v[70:71]
	v_pk_fma_f32 v[58:59], v[56:57], v[132:133], v[86:87]
	v_cvt_pk_bf16_f32 v56, v60, v61
	v_cvt_pk_bf16_f32 v57, v62, v63
	s_nop 0
	v_cvt_pk_bf16_f32 v58, v58, v59
	v_cvt_pk_bf16_f32 v59, v68, v69
	v_add_co_u32_e32 v68, vcc, s91, v146
	global_store_dwordx4 v[84:85], v[56:59], off
	s_nop 0
	v_addc_co_u32_e32 v69, vcc, 0, v147, vcc
	s_waitcnt vmcnt(15)
	v_lshlrev_b32_e32 v70, 16, v236
	v_and_b32_e32 v71, 0xffff0000, v236
	v_lshlrev_b32_e32 v60, 16, v237
	v_and_b32_e32 v61, 0xffff0000, v237
	v_lshlrev_b32_e32 v82, 16, v238
	v_and_b32_e32 v83, 0xffff0000, v238
	v_lshlrev_b32_e32 v62, 16, v239
	v_and_b32_e32 v63, 0xffff0000, v239
	v_pk_fma_f32 v[54:55], v[54:55], v[110:111], v[60:61]
	v_pk_fma_f32 v[52:53], v[52:53], v[108:109], v[70:71]
	v_pk_fma_f32 v[60:61], v[46:47], v[106:107], v[62:63]
	v_pk_fma_f32 v[46:47], v[44:45], v[104:105], v[82:83]
	v_cvt_pk_bf16_f32 v44, v52, v53
	v_cvt_pk_bf16_f32 v45, v54, v55
	s_nop 0
	v_cvt_pk_bf16_f32 v46, v46, v47
	v_cvt_pk_bf16_f32 v47, v60, v61
	v_lshl_add_u64 v[60:61], v[146:147], 0, s[4:5]
	global_store_dwordx4 v[80:81], v[44:47], off offset:256
	s_mov_b32 s4, 0xa0000
	s_waitcnt vmcnt(15)
	v_lshlrev_b32_e32 v62, 16, v240
	v_and_b32_e32 v63, 0xffff0000, v240
	v_lshlrev_b32_e32 v52, 16, v241
	v_and_b32_e32 v53, 0xffff0000, v241
	v_lshlrev_b32_e32 v70, 16, v242
	v_and_b32_e32 v71, 0xffff0000, v242
	v_lshlrev_b32_e32 v54, 16, v243
	v_and_b32_e32 v55, 0xffff0000, v243
	v_pk_fma_f32 v[50:51], v[50:51], v[138:139], v[52:53]
	v_pk_fma_f32 v[48:49], v[48:49], v[136:137], v[62:63]
	v_pk_fma_f32 v[52:53], v[42:43], v[134:135], v[54:55]
	v_pk_fma_f32 v[42:43], v[40:41], v[132:133], v[70:71]
	v_cvt_pk_bf16_f32 v40, v48, v49
	v_cvt_pk_bf16_f32 v41, v50, v51
	s_nop 0
	v_cvt_pk_bf16_f32 v42, v42, v43
	v_cvt_pk_bf16_f32 v43, v52, v53
	v_add_co_u32_e32 v52, vcc, s4, v146
	global_store_dwordx4 v[68:69], v[40:43], off
	s_nop 0
	v_addc_co_u32_e32 v53, vcc, 0, v147, vcc
	s_mov_b64 s[4:5], 0xa0000
	s_waitcnt vmcnt(14)
	v_lshlrev_b32_e32 v54, 16, v186
	v_and_b32_e32 v55, 0xffff0000, v186
	v_lshlrev_b32_e32 v48, 16, v187
	v_and_b32_e32 v49, 0xffff0000, v187
	v_lshlrev_b32_e32 v62, 16, v188
	v_and_b32_e32 v63, 0xffff0000, v188
	v_lshlrev_b32_e32 v50, 16, v189
	v_and_b32_e32 v51, 0xffff0000, v189
	v_pk_fma_f32 v[38:39], v[38:39], v[110:111], v[48:49]
	v_pk_fma_f32 v[48:49], v[30:31], v[106:107], v[50:51]
	v_pk_fma_f32 v[30:31], v[28:29], v[104:105], v[62:63]
	v_pk_fma_f32 v[36:37], v[36:37], v[108:109], v[54:55]
	s_nop 0
	v_cvt_pk_bf16_f32 v28, v36, v37
	v_cvt_pk_bf16_f32 v29, v38, v39
	v_cvt_pk_bf16_f32 v30, v30, v31
	v_cvt_pk_bf16_f32 v31, v48, v49
	global_store_dwordx4 v[60:61], v[28:31], off offset:256
	v_lshl_add_u64 v[48:49], v[146:147], 0, s[4:5]
	s_mov_b32 s4, 0xb0000
	s_waitcnt vmcnt(13)
	v_lshlrev_b32_e32 v50, 16, v190
	v_and_b32_e32 v51, 0xffff0000, v190
	v_lshlrev_b32_e32 v36, 16, v191
	v_and_b32_e32 v37, 0xffff0000, v191
	v_lshlrev_b32_e32 v54, 16, v192
	v_and_b32_e32 v55, 0xffff0000, v192
	v_lshlrev_b32_e32 v38, 16, v193
	v_and_b32_e32 v39, 0xffff0000, v193
	v_pk_fma_f32 v[34:35], v[34:35], v[138:139], v[36:37]
	v_pk_fma_f32 v[32:33], v[32:33], v[136:137], v[50:51]
	v_pk_fma_f32 v[36:37], v[26:27], v[134:135], v[38:39]
	v_pk_fma_f32 v[26:27], v[24:25], v[132:133], v[54:55]
	v_cvt_pk_bf16_f32 v24, v32, v33
	v_cvt_pk_bf16_f32 v25, v34, v35
	s_nop 0
	v_cvt_pk_bf16_f32 v26, v26, v27
	v_cvt_pk_bf16_f32 v27, v36, v37
	v_add_co_u32_e32 v36, vcc, s4, v146
	global_store_dwordx4 v[52:53], v[24:27], off
	s_nop 0
	v_addc_co_u32_e32 v37, vcc, 0, v147, vcc
	s_mov_b64 s[4:5], 0xb0000
	v_cmp_gt_u32_e32 vcc, 16, v180
	s_waitcnt vmcnt(12)
	v_lshlrev_b32_e32 v38, 16, v200
	v_and_b32_e32 v39, 0xffff0000, v200
	v_lshlrev_b32_e32 v32, 16, v201
	v_and_b32_e32 v33, 0xffff0000, v201
	v_lshlrev_b32_e32 v50, 16, v202
	v_and_b32_e32 v51, 0xffff0000, v202
	v_lshlrev_b32_e32 v34, 16, v203
	v_and_b32_e32 v35, 0xffff0000, v203
	v_pk_fma_f32 v[22:23], v[22:23], v[110:111], v[32:33]
	v_pk_fma_f32 v[20:21], v[20:21], v[108:109], v[38:39]
	v_pk_fma_f32 v[32:33], v[14:15], v[106:107], v[34:35]
	v_pk_fma_f32 v[14:15], v[12:13], v[104:105], v[50:51]
	v_cvt_pk_bf16_f32 v12, v20, v21
	v_cvt_pk_bf16_f32 v13, v22, v23
	s_nop 0
	v_cvt_pk_bf16_f32 v14, v14, v15
	v_cvt_pk_bf16_f32 v15, v32, v33
	v_lshl_add_u64 v[32:33], v[146:147], 0, s[4:5]
	global_store_dwordx4 v[48:49], v[12:15], off offset:256
	v_readlane_b32 s4, v254, 29
	s_waitcnt vmcnt(11)
	v_lshlrev_b32_e32 v34, 16, v204
	v_and_b32_e32 v35, 0xffff0000, v204
	v_lshlrev_b32_e32 v20, 16, v205
	v_and_b32_e32 v21, 0xffff0000, v205
	v_lshlrev_b32_e32 v38, 16, v206
	v_and_b32_e32 v39, 0xffff0000, v206
	v_lshlrev_b32_e32 v22, 16, v207
	v_and_b32_e32 v23, 0xffff0000, v207
	v_pk_fma_f32 v[18:19], v[18:19], v[138:139], v[20:21]
	v_pk_fma_f32 v[20:21], v[10:11], v[134:135], v[22:23]
	v_pk_fma_f32 v[10:11], v[8:9], v[132:133], v[38:39]
	v_pk_fma_f32 v[16:17], v[16:17], v[136:137], v[34:35]
	v_mul_f32_e32 v34, v173, v173
	v_cvt_pk_bf16_f32 v8, v16, v17
	v_cvt_pk_bf16_f32 v9, v18, v19
	v_cvt_pk_bf16_f32 v10, v10, v11
	v_cvt_pk_bf16_f32 v11, v20, v21
	v_mul_f32_e32 v18, v177, v177
	v_mul_f32_e32 v19, v175, v175
	v_fmac_f32_e32 v18, v176, v176
	v_fmac_f32_e32 v19, v174, v174
	v_mul_f32_e32 v35, v171, v171
	v_fmac_f32_e32 v34, v172, v172
	v_add_f32_e32 v18, v18, v19
	v_fmac_f32_e32 v35, v170, v170
	v_add_f32_e32 v18, v18, v34
	v_mul_f32_e32 v19, v169, v169
	v_mul_f32_e32 v34, v167, v167
	v_add_f32_e32 v18, v18, v35
	v_mul_f32_e32 v35, v165, v165
	v_fmac_f32_e32 v19, v168, v168
	v_fmac_f32_e32 v34, v166, v166
	v_mul_f32_e32 v38, v163, v163
	v_fmac_f32_e32 v35, v164, v164
	v_add_f32_e32 v19, v19, v34
	v_fmac_f32_e32 v38, v162, v162
	v_add_f32_e32 v19, v19, v35
	v_lshlrev_b32_e32 v17, 2, v180
	v_add_f32_e32 v19, v19, v38
	v_xor_b32_e32 v16, 64, v17
	v_add_f32_e32 v18, v18, v19
	ds_bpermute_b32 v19, v16, v18
	v_xor_b32_e32 v17, 0x80, v17
	global_store_dwordx4 v[36:37], v[8:11], off
	s_waitcnt lgkmcnt(0)
	v_add_f32_e32 v18, v18, v19
	s_waitcnt vmcnt(10)
	v_lshlrev_b32_e32 v34, 16, v208
	v_and_b32_e32 v35, 0xffff0000, v208
	v_lshlrev_b32_e32 v20, 16, v209
	v_and_b32_e32 v21, 0xffff0000, v209
	v_lshlrev_b32_e32 v36, 16, v210
	v_and_b32_e32 v37, 0xffff0000, v210
	v_lshlrev_b32_e32 v22, 16, v211
	v_and_b32_e32 v23, 0xffff0000, v211
	v_pk_fma_f32 v[4:5], v[4:5], v[108:109], v[34:35]
	v_pk_fma_f32 v[6:7], v[6:7], v[110:111], v[20:21]
	v_pk_fma_f32 v[20:21], v[2:3], v[106:107], v[22:23]
	v_pk_fma_f32 v[2:3], v[0:1], v[104:105], v[36:37]
	v_cvt_pk_bf16_f32 v0, v4, v5
	ds_bpermute_b32 v5, v17, v18
	v_cvt_pk_bf16_f32 v1, v6, v7
	v_cvt_pk_bf16_f32 v2, v2, v3
	v_cvt_pk_bf16_f32 v3, v20, v21
	global_store_dwordx4 v[32:33], v[0:3], off offset:256
	v_lshl_add_u32 v4, v180, 4, s4
	s_and_saveexec_b64 s[4:5], vcc
	s_mov_b32 s72, 0x60000
	v_readlane_b32 s85, v255, 11
	s_cbranch_execz .LBB0_532
	s_waitcnt lgkmcnt(0)
	v_add_f32_e32 v5, v18, v5
	ds_write_b32 v4, v5

.LBB0_1053:
	s_lshl_b32 s37, s82, 8
	v_mbcnt_lo_u32_b32 v180, -1, 0
	v_mbcnt_hi_u32_b32 v180, -1, v180
	s_add_i32 s4, s37, s64
	v_and_b32_e32 v178, 15, v180
	s_lshl_b32 s5, s10, 8
	v_readlane_b32 s8, v254, 25
	v_ashrrev_i32_e32 v104, 1, v180
	s_or_b32 s5, s5, s8
	v_and_b32_e32 v104, -8, v104
	v_or_b32_e32 v148, s4, v178
	v_add_u32_e32 v144, s5, v104
	v_ashrrev_i32_e32 v149, 31, v148
	v_ashrrev_i32_e32 v145, 31, v144
	v_lshlrev_b64 v[104:105], 12, v[148:149]
	v_lshl_add_u64 v[104:105], s[20:21], 0, v[104:105]
	v_lshlrev_b64 v[150:151], 1, v[144:145]
	v_lshl_add_u64 v[146:147], v[104:105], 0, v[150:151]
	global_load_dwordx4 v[152:155], v[146:147], off
	v_lshl_add_u64 v[108:109], v[144:145], 2, s[22:23]
	global_load_dwordx4 v[136:139], v[108:109], off
	global_load_dwordx4 v[132:135], v[108:109], off offset:16
	global_load_dwordx4 v[104:107], v[108:109], off offset:528
	s_nop 0
	global_load_dwordx4 v[108:111], v[108:109], off offset:512
	s_mov_b64 s[4:5], 0x80000
	s_mov_b64 s[98:99], 0x10000
	v_lshl_add_u64 v[244:245], v[146:147], 0, s[98:99]
	s_mov_b64 s[98:99], 0x20000
	v_lshl_add_u64 v[246:247], v[146:147], 0, s[98:99]
	s_mov_b64 s[98:99], 0x30000
	v_lshl_add_u64 v[248:249], v[146:147], 0, s[98:99]
	s_mov_b64 s[98:99], 0x80000
	v_lshl_add_u64 v[250:251], v[146:147], 0, s[98:99]
	s_mov_b64 s[98:99], 0x90000
	v_lshl_add_u64 v[252:253], v[146:147], 0, s[98:99]
	s_mov_b64 s[98:99], 0xa0000
	v_lshl_add_u64 v[194:195], v[146:147], 0, s[98:99]
	s_mov_b64 s[98:99], 0xb0000
	v_lshl_add_u64 v[212:213], v[146:147], 0, s[98:99]
	global_load_dwordx4 v[186:189], v[146:147], off offset:256
	global_load_dwordx4 v[190:193], v[244:245], off
	global_load_dwordx4 v[200:203], v[244:245], off offset:256
	global_load_dwordx4 v[204:207], v[246:247], off
	global_load_dwordx4 v[208:211], v[246:247], off offset:256
	global_load_dwordx4 v[224:227], v[248:249], off
	global_load_dwordx4 v[228:231], v[248:249], off offset:256
	global_load_dwordx4 v[232:235], v[250:251], off
	global_load_dwordx4 v[236:239], v[250:251], off offset:256
	global_load_dwordx4 v[240:243], v[252:253], off
	s_waitcnt vmcnt(14)
	v_lshlrev_b32_e32 v156, 16, v152
	v_and_b32_e32 v157, 0xffff0000, v152
	v_lshlrev_b32_e32 v152, 16, v153
	v_and_b32_e32 v153, 0xffff0000, v153
	v_lshlrev_b32_e32 v158, 16, v154
	v_and_b32_e32 v159, 0xffff0000, v154
	v_lshlrev_b32_e32 v154, 16, v155
	v_and_b32_e32 v155, 0xffff0000, v155
	s_waitcnt vmcnt(13)
	v_pk_fma_f32 v[142:143], v[142:143], v[138:139], v[152:153]
	v_pk_fma_f32 v[140:141], v[140:141], v[136:137], v[156:157]
	s_waitcnt vmcnt(12)
	v_pk_fma_f32 v[152:153], v[130:131], v[134:135], v[154:155]
	v_pk_fma_f32 v[130:131], v[128:129], v[132:133], v[158:159]
	v_cvt_pk_bf16_f32 v128, v140, v141
	v_cvt_pk_bf16_f32 v129, v142, v143
	s_nop 0
	v_cvt_pk_bf16_f32 v130, v130, v131
	v_cvt_pk_bf16_f32 v131, v152, v153
	v_or_b32_e32 v152, 16, v148
	v_ashrrev_i32_e32 v153, 31, v152
	v_lshlrev_b64 v[152:153], 12, v[152:153]
	v_lshl_add_u64 v[152:153], s[20:21], 0, v[152:153]
	v_lshl_add_u64 v[152:153], v[152:153], 0, v[150:151]
	global_store_dwordx4 v[146:147], v[128:131], off
	v_and_b32_e32 v177, 0xffff0000, v128
	v_and_b32_e32 v175, 0xffff0000, v129
	v_lshlrev_b32_e32 v176, 16, v128
	v_lshlrev_b32_e32 v174, 16, v129
	v_and_b32_e32 v173, 0xffff0000, v130
	v_lshlrev_b32_e32 v172, 16, v130
	v_and_b32_e32 v171, 0xffff0000, v131
	v_lshlrev_b32_e32 v170, 16, v131
	s_waitcnt vmcnt(10)
	v_lshlrev_b32_e32 v154, 16, v186
	v_and_b32_e32 v155, 0xffff0000, v186
	v_lshlrev_b32_e32 v140, 16, v187
	v_and_b32_e32 v141, 0xffff0000, v187
	v_lshlrev_b32_e32 v156, 16, v188
	v_and_b32_e32 v157, 0xffff0000, v188
	v_lshlrev_b32_e32 v142, 16, v189
	v_and_b32_e32 v143, 0xffff0000, v189
	global_load_dwordx4 v[186:189], v[252:253], off offset:256
	v_pk_fma_f32 v[122:123], v[122:123], v[110:111], v[140:141]
	v_pk_fma_f32 v[120:121], v[120:121], v[108:109], v[154:155]
	v_pk_fma_f32 v[140:141], v[118:119], v[106:107], v[142:143]
	v_pk_fma_f32 v[118:119], v[116:117], v[104:105], v[156:157]
	v_cvt_pk_bf16_f32 v116, v120, v121
	v_cvt_pk_bf16_f32 v117, v122, v123
	s_nop 0
	v_cvt_pk_bf16_f32 v118, v118, v119
	v_cvt_pk_bf16_f32 v119, v140, v141
	v_and_b32_e32 v169, 0xffff0000, v116
	global_store_dwordx4 v[146:147], v[116:119], off offset:256
	v_and_b32_e32 v167, 0xffff0000, v117
	v_lshlrev_b32_e32 v168, 16, v116
	v_lshlrev_b32_e32 v166, 16, v117
	v_and_b32_e32 v165, 0xffff0000, v118
	v_lshlrev_b32_e32 v164, 16, v118
	v_and_b32_e32 v163, 0xffff0000, v119
	v_lshlrev_b32_e32 v162, 16, v119
	s_waitcnt vmcnt(11)
	v_lshlrev_b32_e32 v140, 16, v190
	v_and_b32_e32 v141, 0xffff0000, v190
	v_lshlrev_b32_e32 v120, 16, v191
	v_and_b32_e32 v121, 0xffff0000, v191
	v_lshlrev_b32_e32 v142, 16, v192
	v_and_b32_e32 v143, 0xffff0000, v192
	v_lshlrev_b32_e32 v122, 16, v193
	v_and_b32_e32 v123, 0xffff0000, v193
	global_load_dwordx4 v[190:193], v[194:195], off
	v_pk_fma_f32 v[120:121], v[126:127], v[138:139], v[120:121]
	v_pk_fma_f32 v[122:123], v[114:115], v[134:135], v[122:123]
	v_pk_fma_f32 v[114:115], v[112:113], v[132:133], v[142:143]
	v_pk_fma_f32 v[124:125], v[124:125], v[136:137], v[140:141]
	s_nop 0
	v_cvt_pk_bf16_f32 v112, v124, v125
	v_cvt_pk_bf16_f32 v113, v120, v121
	v_cvt_pk_bf16_f32 v114, v114, v115
	v_cvt_pk_bf16_f32 v115, v122, v123
	v_or_b32_e32 v124, 32, v148
	v_ashrrev_i32_e32 v125, 31, v124
	v_lshlrev_b64 v[124:125], 12, v[124:125]
	v_lshl_add_u64 v[124:125], s[20:21], 0, v[124:125]
	global_store_dwordx4 v[152:153], v[112:115], off
	v_lshl_add_u64 v[124:125], v[124:125], 0, v[150:151]
	s_waitcnt vmcnt(12)
	v_lshlrev_b32_e32 v126, 16, v200
	v_and_b32_e32 v127, 0xffff0000, v200
	v_lshlrev_b32_e32 v120, 16, v201
	v_and_b32_e32 v121, 0xffff0000, v201
	v_lshlrev_b32_e32 v140, 16, v202
	v_and_b32_e32 v141, 0xffff0000, v202
	v_lshlrev_b32_e32 v122, 16, v203
	v_and_b32_e32 v123, 0xffff0000, v203
	global_load_dwordx4 v[200:203], v[194:195], off offset:256
	v_pk_fma_f32 v[102:103], v[102:103], v[110:111], v[120:121]
	v_pk_fma_f32 v[120:121], v[94:95], v[106:107], v[122:123]
	v_pk_fma_f32 v[94:95], v[92:93], v[104:105], v[140:141]
	v_pk_fma_f32 v[100:101], v[100:101], v[108:109], v[126:127]
	s_nop 0
	v_cvt_pk_bf16_f32 v92, v100, v101
	v_cvt_pk_bf16_f32 v93, v102, v103
	v_cvt_pk_bf16_f32 v94, v94, v95
	v_cvt_pk_bf16_f32 v95, v120, v121
	global_store_dwordx4 v[152:153], v[92:95], off offset:256
	s_waitcnt vmcnt(13)
	v_lshlrev_b32_e32 v120, 16, v204
	v_and_b32_e32 v121, 0xffff0000, v204
	v_lshlrev_b32_e32 v100, 16, v205
	v_and_b32_e32 v101, 0xffff0000, v205
	v_lshlrev_b32_e32 v122, 16, v206
	v_and_b32_e32 v123, 0xffff0000, v206
	v_lshlrev_b32_e32 v102, 16, v207
	v_and_b32_e32 v103, 0xffff0000, v207
	global_load_dwordx4 v[204:207], v[212:213], off
	v_pk_fma_f32 v[98:99], v[98:99], v[138:139], v[100:101]
	v_pk_fma_f32 v[96:97], v[96:97], v[136:137], v[120:121]
	v_pk_fma_f32 v[100:101], v[90:91], v[134:135], v[102:103]
	v_pk_fma_f32 v[90:91], v[88:89], v[132:133], v[122:123]
	v_cvt_pk_bf16_f32 v88, v96, v97
	v_cvt_pk_bf16_f32 v89, v98, v99
	s_nop 0
	v_cvt_pk_bf16_f32 v90, v90, v91
	v_cvt_pk_bf16_f32 v91, v100, v101
	v_or_b32_e32 v100, 48, v148
	v_ashrrev_i32_e32 v101, 31, v100
	v_lshlrev_b64 v[100:101], 12, v[100:101]
	v_lshl_add_u64 v[100:101], s[20:21], 0, v[100:101]
	v_lshl_add_u64 v[100:101], v[100:101], 0, v[150:151]
	global_store_dwordx4 v[124:125], v[88:91], off
	s_waitcnt vmcnt(14)
	v_lshlrev_b32_e32 v102, 16, v208
	v_and_b32_e32 v103, 0xffff0000, v208
	v_lshlrev_b32_e32 v96, 16, v209
	v_and_b32_e32 v97, 0xffff0000, v209
	v_lshlrev_b32_e32 v120, 16, v210
	v_and_b32_e32 v121, 0xffff0000, v210
	v_lshlrev_b32_e32 v98, 16, v211
	v_and_b32_e32 v99, 0xffff0000, v211
	global_load_dwordx4 v[208:211], v[212:213], off offset:256
	v_pk_fma_f32 v[82:83], v[82:83], v[110:111], v[96:97]
	v_pk_fma_f32 v[80:81], v[80:81], v[108:109], v[102:103]
	v_pk_fma_f32 v[96:97], v[78:79], v[106:107], v[98:99]
	v_pk_fma_f32 v[78:79], v[76:77], v[104:105], v[120:121]
	v_cvt_pk_bf16_f32 v76, v80, v81
	v_cvt_pk_bf16_f32 v77, v82, v83
	s_nop 0
	v_cvt_pk_bf16_f32 v78, v78, v79
	v_cvt_pk_bf16_f32 v79, v96, v97
	s_waitcnt vmcnt(14)
	v_lshlrev_b32_e32 v96, 16, v224
	v_and_b32_e32 v97, 0xffff0000, v224
	v_lshlrev_b32_e32 v80, 16, v225
	v_and_b32_e32 v81, 0xffff0000, v225
	v_lshlrev_b32_e32 v98, 16, v226
	v_and_b32_e32 v99, 0xffff0000, v226
	v_lshlrev_b32_e32 v82, 16, v227
	v_and_b32_e32 v83, 0xffff0000, v227
	v_pk_fma_f32 v[80:81], v[86:87], v[138:139], v[80:81]
	v_pk_fma_f32 v[82:83], v[74:75], v[134:135], v[82:83]
	v_pk_fma_f32 v[74:75], v[72:73], v[132:133], v[98:99]
	global_store_dwordx4 v[124:125], v[76:79], off offset:256
	v_pk_fma_f32 v[84:85], v[84:85], v[136:137], v[96:97]
	s_nop 0
	v_cvt_pk_bf16_f32 v72, v84, v85
	v_cvt_pk_bf16_f32 v73, v80, v81
	v_cvt_pk_bf16_f32 v74, v74, v75
	v_cvt_pk_bf16_f32 v75, v82, v83
	v_add_co_u32_e32 v84, vcc, s90, v146
	global_store_dwordx4 v[100:101], v[72:75], off
	s_nop 0
	v_addc_co_u32_e32 v85, vcc, 0, v147, vcc
	s_waitcnt vmcnt(15)
	v_lshlrev_b32_e32 v86, 16, v228
	v_and_b32_e32 v87, 0xffff0000, v228
	v_lshlrev_b32_e32 v80, 16, v229
	v_and_b32_e32 v81, 0xffff0000, v229
	v_lshlrev_b32_e32 v96, 16, v230
	v_and_b32_e32 v97, 0xffff0000, v230
	v_lshlrev_b32_e32 v82, 16, v231
	v_and_b32_e32 v83, 0xffff0000, v231
	v_pk_fma_f32 v[70:71], v[70:71], v[110:111], v[80:81]
	v_pk_fma_f32 v[80:81], v[66:67], v[106:107], v[82:83]
	v_pk_fma_f32 v[66:67], v[64:65], v[104:105], v[96:97]
	v_pk_fma_f32 v[68:69], v[68:69], v[108:109], v[86:87]
	s_nop 0
	v_cvt_pk_bf16_f32 v64, v68, v69
	v_cvt_pk_bf16_f32 v65, v70, v71
	v_cvt_pk_bf16_f32 v66, v66, v67
	v_cvt_pk_bf16_f32 v67, v80, v81
	global_store_dwordx4 v[100:101], v[64:67], off offset:256
	v_lshl_add_u64 v[80:81], v[146:147], 0, s[4:5]
	s_mov_b64 s[4:5], 0x90000
	s_waitcnt vmcnt(15)
	v_lshlrev_b32_e32 v82, 16, v232
	v_and_b32_e32 v83, 0xffff0000, v232
	v_lshlrev_b32_e32 v68, 16, v233
	v_and_b32_e32 v69, 0xffff0000, v233
	v_lshlrev_b32_e32 v86, 16, v234
	v_and_b32_e32 v87, 0xffff0000, v234
	v_lshlrev_b32_e32 v70, 16, v235
	v_and_b32_e32 v71, 0xffff0000, v235
	v_pk_fma_f32 v[62:63], v[62:63], v[138:139], v[68:69]
	v_pk_fma_f32 v[60:61], v[60:61], v[136:137], v[82:83]
	v_pk_fma_f32 v[68:69], v[58:59], v[134:135], v[70:71]
	v_pk_fma_f32 v[58:59], v[56:57], v[132:133], v[86:87]
	v_cvt_pk_bf16_f32 v56, v60, v61
	v_cvt_pk_bf16_f32 v57, v62, v63
	s_nop 0
	v_cvt_pk_bf16_f32 v58, v58, v59
	v_cvt_pk_bf16_f32 v59, v68, v69
	v_add_co_u32_e32 v68, vcc, s91, v146
	global_store_dwordx4 v[84:85], v[56:59], off
	s_nop 0
	v_addc_co_u32_e32 v69, vcc, 0, v147, vcc
	s_waitcnt vmcnt(15)
	v_lshlrev_b32_e32 v70, 16, v236
	v_and_b32_e32 v71, 0xffff0000, v236
	v_lshlrev_b32_e32 v60, 16, v237
	v_and_b32_e32 v61, 0xffff0000, v237
	v_lshlrev_b32_e32 v82, 16, v238
	v_and_b32_e32 v83, 0xffff0000, v238
	v_lshlrev_b32_e32 v62, 16, v239
	v_and_b32_e32 v63, 0xffff0000, v239
	v_pk_fma_f32 v[54:55], v[54:55], v[110:111], v[60:61]
	v_pk_fma_f32 v[52:53], v[52:53], v[108:109], v[70:71]
	v_pk_fma_f32 v[60:61], v[46:47], v[106:107], v[62:63]
	v_pk_fma_f32 v[46:47], v[44:45], v[104:105], v[82:83]
	v_cvt_pk_bf16_f32 v44, v52, v53
	v_cvt_pk_bf16_f32 v45, v54, v55
	s_nop 0
	v_cvt_pk_bf16_f32 v46, v46, v47
	v_cvt_pk_bf16_f32 v47, v60, v61
	v_lshl_add_u64 v[60:61], v[146:147], 0, s[4:5]
	global_store_dwordx4 v[80:81], v[44:47], off offset:256
	s_mov_b32 s4, 0xa0000
	s_waitcnt vmcnt(15)
	v_lshlrev_b32_e32 v62, 16, v240
	v_and_b32_e32 v63, 0xffff0000, v240
	v_lshlrev_b32_e32 v52, 16, v241
	v_and_b32_e32 v53, 0xffff0000, v241
	v_lshlrev_b32_e32 v70, 16, v242
	v_and_b32_e32 v71, 0xffff0000, v242
	v_lshlrev_b32_e32 v54, 16, v243
	v_and_b32_e32 v55, 0xffff0000, v243
	v_pk_fma_f32 v[50:51], v[50:51], v[138:139], v[52:53]
	v_pk_fma_f32 v[48:49], v[48:49], v[136:137], v[62:63]
	v_pk_fma_f32 v[52:53], v[42:43], v[134:135], v[54:55]
	v_pk_fma_f32 v[42:43], v[40:41], v[132:133], v[70:71]
	v_cvt_pk_bf16_f32 v40, v48, v49
	v_cvt_pk_bf16_f32 v41, v50, v51
	s_nop 0
	v_cvt_pk_bf16_f32 v42, v42, v43
	v_cvt_pk_bf16_f32 v43, v52, v53
	v_add_co_u32_e32 v52, vcc, s4, v146
	global_store_dwordx4 v[68:69], v[40:43], off
	s_nop 0
	v_addc_co_u32_e32 v53, vcc, 0, v147, vcc
	s_mov_b64 s[4:5], 0xa0000
	s_waitcnt vmcnt(14)
	v_lshlrev_b32_e32 v54, 16, v186
	v_and_b32_e32 v55, 0xffff0000, v186
	v_lshlrev_b32_e32 v48, 16, v187
	v_and_b32_e32 v49, 0xffff0000, v187
	v_lshlrev_b32_e32 v62, 16, v188
	v_and_b32_e32 v63, 0xffff0000, v188
	v_lshlrev_b32_e32 v50, 16, v189
	v_and_b32_e32 v51, 0xffff0000, v189
	v_pk_fma_f32 v[38:39], v[38:39], v[110:111], v[48:49]
	v_pk_fma_f32 v[48:49], v[30:31], v[106:107], v[50:51]
	v_pk_fma_f32 v[30:31], v[28:29], v[104:105], v[62:63]
	v_pk_fma_f32 v[36:37], v[36:37], v[108:109], v[54:55]
	s_nop 0
	v_cvt_pk_bf16_f32 v28, v36, v37
	v_cvt_pk_bf16_f32 v29, v38, v39
	v_cvt_pk_bf16_f32 v30, v30, v31
	v_cvt_pk_bf16_f32 v31, v48, v49
	global_store_dwordx4 v[60:61], v[28:31], off offset:256
	v_lshl_add_u64 v[48:49], v[146:147], 0, s[4:5]
	s_mov_b32 s4, 0xb0000
	s_waitcnt vmcnt(13)
	v_lshlrev_b32_e32 v50, 16, v190
	v_and_b32_e32 v51, 0xffff0000, v190
	v_lshlrev_b32_e32 v36, 16, v191
	v_and_b32_e32 v37, 0xffff0000, v191
	v_lshlrev_b32_e32 v54, 16, v192
	v_and_b32_e32 v55, 0xffff0000, v192
	v_lshlrev_b32_e32 v38, 16, v193
	v_and_b32_e32 v39, 0xffff0000, v193
	v_pk_fma_f32 v[34:35], v[34:35], v[138:139], v[36:37]
	v_pk_fma_f32 v[32:33], v[32:33], v[136:137], v[50:51]
	v_pk_fma_f32 v[36:37], v[26:27], v[134:135], v[38:39]
	v_pk_fma_f32 v[26:27], v[24:25], v[132:133], v[54:55]
	v_cvt_pk_bf16_f32 v24, v32, v33
	v_cvt_pk_bf16_f32 v25, v34, v35
	s_nop 0
	v_cvt_pk_bf16_f32 v26, v26, v27
	v_cvt_pk_bf16_f32 v27, v36, v37
	v_add_co_u32_e32 v36, vcc, s4, v146
	global_store_dwordx4 v[52:53], v[24:27], off
	s_nop 0
	v_addc_co_u32_e32 v37, vcc, 0, v147, vcc
	s_mov_b64 s[4:5], 0xb0000
	v_cmp_gt_u32_e32 vcc, 16, v180
	s_waitcnt vmcnt(12)
	v_lshlrev_b32_e32 v38, 16, v200
	v_and_b32_e32 v39, 0xffff0000, v200
	v_lshlrev_b32_e32 v32, 16, v201
	v_and_b32_e32 v33, 0xffff0000, v201
	v_lshlrev_b32_e32 v50, 16, v202
	v_and_b32_e32 v51, 0xffff0000, v202
	v_lshlrev_b32_e32 v34, 16, v203
	v_and_b32_e32 v35, 0xffff0000, v203
	v_pk_fma_f32 v[22:23], v[22:23], v[110:111], v[32:33]
	v_pk_fma_f32 v[20:21], v[20:21], v[108:109], v[38:39]
	v_pk_fma_f32 v[32:33], v[14:15], v[106:107], v[34:35]
	v_pk_fma_f32 v[14:15], v[12:13], v[104:105], v[50:51]
	v_cvt_pk_bf16_f32 v12, v20, v21
	v_cvt_pk_bf16_f32 v13, v22, v23
	s_nop 0
	v_cvt_pk_bf16_f32 v14, v14, v15
	v_cvt_pk_bf16_f32 v15, v32, v33
	v_lshl_add_u64 v[32:33], v[146:147], 0, s[4:5]
	global_store_dwordx4 v[48:49], v[12:15], off offset:256
	v_readlane_b32 s4, v254, 29
	s_waitcnt vmcnt(11)
	v_lshlrev_b32_e32 v34, 16, v204
	v_and_b32_e32 v35, 0xffff0000, v204
	v_lshlrev_b32_e32 v20, 16, v205
	v_and_b32_e32 v21, 0xffff0000, v205
	v_lshlrev_b32_e32 v38, 16, v206
	v_and_b32_e32 v39, 0xffff0000, v206
	v_lshlrev_b32_e32 v22, 16, v207
	v_and_b32_e32 v23, 0xffff0000, v207
	v_pk_fma_f32 v[18:19], v[18:19], v[138:139], v[20:21]
	v_pk_fma_f32 v[20:21], v[10:11], v[134:135], v[22:23]
	v_pk_fma_f32 v[10:11], v[8:9], v[132:133], v[38:39]
	v_pk_fma_f32 v[16:17], v[16:17], v[136:137], v[34:35]
	v_mul_f32_e32 v34, v173, v173
	v_cvt_pk_bf16_f32 v8, v16, v17
	v_cvt_pk_bf16_f32 v9, v18, v19
	v_cvt_pk_bf16_f32 v10, v10, v11
	v_cvt_pk_bf16_f32 v11, v20, v21
	v_mul_f32_e32 v18, v177, v177
	v_mul_f32_e32 v19, v175, v175
	v_fmac_f32_e32 v18, v176, v176
	v_fmac_f32_e32 v19, v174, v174
	v_mul_f32_e32 v35, v171, v171
	v_fmac_f32_e32 v34, v172, v172
	v_add_f32_e32 v18, v18, v19
	v_fmac_f32_e32 v35, v170, v170
	v_add_f32_e32 v18, v18, v34
	v_mul_f32_e32 v19, v169, v169
	v_mul_f32_e32 v34, v167, v167
	v_add_f32_e32 v18, v18, v35
	v_mul_f32_e32 v35, v165, v165
	v_fmac_f32_e32 v19, v168, v168
	v_fmac_f32_e32 v34, v166, v166
	v_mul_f32_e32 v38, v163, v163
	v_fmac_f32_e32 v35, v164, v164
	v_add_f32_e32 v19, v19, v34
	v_fmac_f32_e32 v38, v162, v162
	v_add_f32_e32 v19, v19, v35
	v_lshlrev_b32_e32 v17, 2, v180
	v_add_f32_e32 v19, v19, v38
	v_xor_b32_e32 v16, 64, v17
	v_add_f32_e32 v18, v18, v19
	ds_bpermute_b32 v19, v16, v18
	v_xor_b32_e32 v17, 0x80, v17
	global_store_dwordx4 v[36:37], v[8:11], off
	s_waitcnt lgkmcnt(0)
	v_add_f32_e32 v18, v18, v19
	s_waitcnt vmcnt(10)
	v_lshlrev_b32_e32 v34, 16, v208
	v_and_b32_e32 v35, 0xffff0000, v208
	v_lshlrev_b32_e32 v20, 16, v209
	v_and_b32_e32 v21, 0xffff0000, v209
	v_lshlrev_b32_e32 v36, 16, v210
	v_and_b32_e32 v37, 0xffff0000, v210
	v_lshlrev_b32_e32 v22, 16, v211
	v_and_b32_e32 v23, 0xffff0000, v211
	v_pk_fma_f32 v[4:5], v[4:5], v[108:109], v[34:35]
	v_pk_fma_f32 v[6:7], v[6:7], v[110:111], v[20:21]
	v_pk_fma_f32 v[20:21], v[2:3], v[106:107], v[22:23]
	v_pk_fma_f32 v[2:3], v[0:1], v[104:105], v[36:37]
	v_cvt_pk_bf16_f32 v0, v4, v5
	ds_bpermute_b32 v5, v17, v18
	v_cvt_pk_bf16_f32 v1, v6, v7
	v_cvt_pk_bf16_f32 v2, v2, v3
	v_cvt_pk_bf16_f32 v3, v20, v21
	global_store_dwordx4 v[32:33], v[0:3], off offset:256
	v_lshl_add_u32 v4, v180, 4, s4
	s_and_saveexec_b64 s[4:5], vcc
	s_mov_b32 s72, 0x60000
	s_cbranch_execz .LBB0_1055
	s_waitcnt lgkmcnt(0)
	v_add_f32_e32 v5, v18, v5
	ds_write_b32 v4, v5

.LBB0_1428:
	s_lshl_b32 s72, s37, 8
	v_mbcnt_lo_u32_b32 v162, -1, 0
	v_mbcnt_hi_u32_b32 v162, -1, v162
	s_add_i32 s4, s72, s64
	v_and_b32_e32 v164, 15, v162
	s_lshl_b32 s5, s14, 8
	v_readlane_b32 s12, v254, 25
	v_ashrrev_i32_e32 v120, 1, v162
	s_or_b32 s5, s5, s12
	v_and_b32_e32 v120, -8, v120
	v_or_b32_e32 v148, s4, v164
	v_add_u32_e32 v144, s5, v120
	v_ashrrev_i32_e32 v149, 31, v148
	v_ashrrev_i32_e32 v145, 31, v144
	v_lshlrev_b64 v[120:121], 12, v[148:149]
	v_lshl_add_u64 v[120:121], s[38:39], 0, v[120:121]
	v_lshlrev_b64 v[150:151], 1, v[144:145]
	v_lshl_add_u64 v[146:147], v[120:121], 0, v[150:151]
	global_load_dwordx4 v[152:155], v[146:147], off
	v_lshl_add_u64 v[124:125], v[144:145], 2, s[40:41]
	global_load_dwordx4 v[136:139], v[124:125], off
	global_load_dwordx4 v[132:135], v[124:125], off offset:16
	global_load_dwordx4 v[120:123], v[124:125], off offset:528
	s_nop 0
	global_load_dwordx4 v[124:127], v[124:125], off offset:512
	s_mov_b64 s[4:5], 0x80000
	s_mov_b64 s[98:99], 0x10000
	v_lshl_add_u64 v[244:245], v[146:147], 0, s[98:99]
	s_mov_b64 s[98:99], 0x20000
	v_lshl_add_u64 v[246:247], v[146:147], 0, s[98:99]
	s_mov_b64 s[98:99], 0x30000
	v_lshl_add_u64 v[248:249], v[146:147], 0, s[98:99]
	s_mov_b64 s[98:99], 0x80000
	v_lshl_add_u64 v[250:251], v[146:147], 0, s[98:99]
	s_mov_b64 s[98:99], 0x90000
	v_lshl_add_u64 v[252:253], v[146:147], 0, s[98:99]
	s_mov_b64 s[98:99], 0xa0000
	v_lshl_add_u64 v[194:195], v[146:147], 0, s[98:99]
	s_mov_b64 s[98:99], 0xb0000
	v_lshl_add_u64 v[212:213], v[146:147], 0, s[98:99]
	global_load_dwordx4 v[186:189], v[146:147], off offset:256
	global_load_dwordx4 v[190:193], v[244:245], off
	global_load_dwordx4 v[200:203], v[244:245], off offset:256
	global_load_dwordx4 v[204:207], v[246:247], off
	global_load_dwordx4 v[208:211], v[246:247], off offset:256
	global_load_dwordx4 v[224:227], v[248:249], off
	global_load_dwordx4 v[228:231], v[248:249], off offset:256
	global_load_dwordx4 v[232:235], v[250:251], off
	global_load_dwordx4 v[236:239], v[250:251], off offset:256
	global_load_dwordx4 v[240:243], v[252:253], off
	s_waitcnt vmcnt(14)
	v_lshlrev_b32_e32 v156, 16, v152
	v_and_b32_e32 v157, 0xffff0000, v152
	v_lshlrev_b32_e32 v152, 16, v153
	v_and_b32_e32 v153, 0xffff0000, v153
	v_lshlrev_b32_e32 v158, 16, v154
	v_and_b32_e32 v159, 0xffff0000, v154
	v_lshlrev_b32_e32 v154, 16, v155
	v_and_b32_e32 v155, 0xffff0000, v155
	s_waitcnt vmcnt(13)
	v_pk_fma_f32 v[142:143], v[142:143], v[138:139], v[152:153]
	v_pk_fma_f32 v[140:141], v[140:141], v[136:137], v[156:157]
	s_waitcnt vmcnt(12)
	v_pk_fma_f32 v[152:153], v[130:131], v[134:135], v[154:155]
	v_pk_fma_f32 v[130:131], v[128:129], v[132:133], v[158:159]
	v_cvt_pk_bf16_f32 v128, v140, v141
	v_cvt_pk_bf16_f32 v129, v142, v143
	s_nop 0
	v_cvt_pk_bf16_f32 v130, v130, v131
	v_cvt_pk_bf16_f32 v131, v152, v153
	v_or_b32_e32 v152, 16, v148
	v_ashrrev_i32_e32 v153, 31, v152
	v_lshlrev_b64 v[152:153], 12, v[152:153]
	v_lshl_add_u64 v[152:153], s[38:39], 0, v[152:153]
	v_lshl_add_u64 v[152:153], v[152:153], 0, v[150:151]
	global_store_dwordx4 v[146:147], v[128:131], off
	s_waitcnt vmcnt(10)
	v_lshlrev_b32_e32 v154, 16, v186
	v_and_b32_e32 v155, 0xffff0000, v186
	v_lshlrev_b32_e32 v140, 16, v187
	v_and_b32_e32 v141, 0xffff0000, v187
	v_lshlrev_b32_e32 v156, 16, v188
	v_and_b32_e32 v157, 0xffff0000, v188
	v_lshlrev_b32_e32 v142, 16, v189
	v_and_b32_e32 v143, 0xffff0000, v189
	global_load_dwordx4 v[186:189], v[252:253], off offset:256
	v_pk_fma_f32 v[114:115], v[114:115], v[126:127], v[140:141]
	v_pk_fma_f32 v[112:113], v[112:113], v[124:125], v[154:155]
	v_pk_fma_f32 v[140:141], v[110:111], v[122:123], v[142:143]
	v_pk_fma_f32 v[110:111], v[108:109], v[120:121], v[156:157]
	v_cvt_pk_bf16_f32 v108, v112, v113
	v_cvt_pk_bf16_f32 v109, v114, v115
	s_nop 0
	v_cvt_pk_bf16_f32 v110, v110, v111
	v_cvt_pk_bf16_f32 v111, v140, v141
	s_waitcnt vmcnt(10)
	v_lshlrev_b32_e32 v140, 16, v190
	v_and_b32_e32 v141, 0xffff0000, v190
	v_lshlrev_b32_e32 v112, 16, v191
	v_and_b32_e32 v113, 0xffff0000, v191
	v_lshlrev_b32_e32 v142, 16, v192
	v_and_b32_e32 v143, 0xffff0000, v192
	v_lshlrev_b32_e32 v114, 16, v193
	v_and_b32_e32 v115, 0xffff0000, v193
	global_load_dwordx4 v[190:193], v[194:195], off
	v_pk_fma_f32 v[112:113], v[118:119], v[138:139], v[112:113]
	v_pk_fma_f32 v[114:115], v[106:107], v[134:135], v[114:115]
	v_pk_fma_f32 v[106:107], v[104:105], v[132:133], v[142:143]
	global_store_dwordx4 v[146:147], v[108:111], off offset:256
	v_pk_fma_f32 v[116:117], v[116:117], v[136:137], v[140:141]
	s_nop 0
	v_cvt_pk_bf16_f32 v104, v116, v117
	v_cvt_pk_bf16_f32 v105, v112, v113
	v_cvt_pk_bf16_f32 v106, v106, v107
	v_cvt_pk_bf16_f32 v107, v114, v115
	v_or_b32_e32 v116, 32, v148
	v_ashrrev_i32_e32 v117, 31, v116
	v_lshlrev_b64 v[116:117], 12, v[116:117]
	v_lshl_add_u64 v[116:117], s[38:39], 0, v[116:117]
	global_store_dwordx4 v[152:153], v[104:107], off
	v_lshl_add_u64 v[116:117], v[116:117], 0, v[150:151]
	s_waitcnt vmcnt(12)
	v_lshlrev_b32_e32 v118, 16, v200
	v_and_b32_e32 v119, 0xffff0000, v200
	v_lshlrev_b32_e32 v112, 16, v201
	v_and_b32_e32 v113, 0xffff0000, v201
	v_lshlrev_b32_e32 v140, 16, v202
	v_and_b32_e32 v141, 0xffff0000, v202
	v_lshlrev_b32_e32 v114, 16, v203
	v_and_b32_e32 v115, 0xffff0000, v203
	global_load_dwordx4 v[200:203], v[194:195], off offset:256
	v_pk_fma_f32 v[102:103], v[102:103], v[126:127], v[112:113]
	v_pk_fma_f32 v[112:113], v[94:95], v[122:123], v[114:115]
	v_pk_fma_f32 v[94:95], v[92:93], v[120:121], v[140:141]
	v_pk_fma_f32 v[100:101], v[100:101], v[124:125], v[118:119]
	s_nop 0
	v_cvt_pk_bf16_f32 v92, v100, v101
	v_cvt_pk_bf16_f32 v93, v102, v103
	v_cvt_pk_bf16_f32 v94, v94, v95
	v_cvt_pk_bf16_f32 v95, v112, v113
	global_store_dwordx4 v[152:153], v[92:95], off offset:256
	s_waitcnt vmcnt(13)
	v_lshlrev_b32_e32 v112, 16, v204
	v_and_b32_e32 v113, 0xffff0000, v204
	v_lshlrev_b32_e32 v100, 16, v205
	v_and_b32_e32 v101, 0xffff0000, v205
	v_lshlrev_b32_e32 v114, 16, v206
	v_and_b32_e32 v115, 0xffff0000, v206
	v_lshlrev_b32_e32 v102, 16, v207
	v_and_b32_e32 v103, 0xffff0000, v207
	global_load_dwordx4 v[204:207], v[212:213], off
	v_pk_fma_f32 v[98:99], v[98:99], v[138:139], v[100:101]
	v_pk_fma_f32 v[96:97], v[96:97], v[136:137], v[112:113]
	v_pk_fma_f32 v[100:101], v[90:91], v[134:135], v[102:103]
	v_pk_fma_f32 v[90:91], v[88:89], v[132:133], v[114:115]
	v_cvt_pk_bf16_f32 v88, v96, v97
	v_cvt_pk_bf16_f32 v89, v98, v99
	s_nop 0
	v_cvt_pk_bf16_f32 v90, v90, v91
	v_cvt_pk_bf16_f32 v91, v100, v101
	v_or_b32_e32 v100, 48, v148
	v_ashrrev_i32_e32 v101, 31, v100
	v_lshlrev_b64 v[100:101], 12, v[100:101]
	v_lshl_add_u64 v[100:101], s[38:39], 0, v[100:101]
	v_lshl_add_u64 v[100:101], v[100:101], 0, v[150:151]
	global_store_dwordx4 v[116:117], v[88:91], off
	s_waitcnt vmcnt(14)
	v_lshlrev_b32_e32 v102, 16, v208
	v_and_b32_e32 v103, 0xffff0000, v208
	v_lshlrev_b32_e32 v96, 16, v209
	v_and_b32_e32 v97, 0xffff0000, v209
	v_lshlrev_b32_e32 v112, 16, v210
	v_and_b32_e32 v113, 0xffff0000, v210
	v_lshlrev_b32_e32 v98, 16, v211
	v_and_b32_e32 v99, 0xffff0000, v211
	global_load_dwordx4 v[208:211], v[212:213], off offset:256
	v_pk_fma_f32 v[82:83], v[82:83], v[126:127], v[96:97]
	v_pk_fma_f32 v[80:81], v[80:81], v[124:125], v[102:103]
	v_pk_fma_f32 v[96:97], v[78:79], v[122:123], v[98:99]
	v_pk_fma_f32 v[78:79], v[76:77], v[120:121], v[112:113]
	v_cvt_pk_bf16_f32 v76, v80, v81
	v_cvt_pk_bf16_f32 v77, v82, v83
	s_nop 0
	v_cvt_pk_bf16_f32 v78, v78, v79
	v_cvt_pk_bf16_f32 v79, v96, v97
	s_waitcnt vmcnt(14)
	v_lshlrev_b32_e32 v96, 16, v224
	v_and_b32_e32 v97, 0xffff0000, v224
	v_lshlrev_b32_e32 v80, 16, v225
	v_and_b32_e32 v81, 0xffff0000, v225
	v_lshlrev_b32_e32 v98, 16, v226
	v_and_b32_e32 v99, 0xffff0000, v226
	v_lshlrev_b32_e32 v82, 16, v227
	v_and_b32_e32 v83, 0xffff0000, v227
	v_pk_fma_f32 v[80:81], v[86:87], v[138:139], v[80:81]
	v_pk_fma_f32 v[82:83], v[74:75], v[134:135], v[82:83]
	v_pk_fma_f32 v[74:75], v[72:73], v[132:133], v[98:99]
	global_store_dwordx4 v[116:117], v[76:79], off offset:256
	v_pk_fma_f32 v[84:85], v[84:85], v[136:137], v[96:97]
	s_nop 0
	v_cvt_pk_bf16_f32 v72, v84, v85
	v_cvt_pk_bf16_f32 v73, v80, v81
	v_cvt_pk_bf16_f32 v74, v74, v75
	v_cvt_pk_bf16_f32 v75, v82, v83
	v_add_co_u32_e32 v84, vcc, s90, v146
	global_store_dwordx4 v[100:101], v[72:75], off
	s_nop 0
	v_addc_co_u32_e32 v85, vcc, 0, v147, vcc
	s_waitcnt vmcnt(15)
	v_lshlrev_b32_e32 v86, 16, v228
	v_and_b32_e32 v87, 0xffff0000, v228
	v_lshlrev_b32_e32 v80, 16, v229
	v_and_b32_e32 v81, 0xffff0000, v229
	v_lshlrev_b32_e32 v96, 16, v230
	v_and_b32_e32 v97, 0xffff0000, v230
	v_lshlrev_b32_e32 v82, 16, v231
	v_and_b32_e32 v83, 0xffff0000, v231
	v_pk_fma_f32 v[70:71], v[70:71], v[126:127], v[80:81]
	v_pk_fma_f32 v[80:81], v[66:67], v[122:123], v[82:83]
	v_pk_fma_f32 v[66:67], v[64:65], v[120:121], v[96:97]
	v_pk_fma_f32 v[68:69], v[68:69], v[124:125], v[86:87]
	s_nop 0
	v_cvt_pk_bf16_f32 v64, v68, v69
	v_cvt_pk_bf16_f32 v65, v70, v71
	v_cvt_pk_bf16_f32 v66, v66, v67
	v_cvt_pk_bf16_f32 v67, v80, v81
	global_store_dwordx4 v[100:101], v[64:67], off offset:256
	v_lshl_add_u64 v[80:81], v[146:147], 0, s[4:5]
	s_mov_b64 s[4:5], 0x90000
	s_waitcnt vmcnt(15)
	v_lshlrev_b32_e32 v82, 16, v232
	v_and_b32_e32 v83, 0xffff0000, v232
	v_lshlrev_b32_e32 v68, 16, v233
	v_and_b32_e32 v69, 0xffff0000, v233
	v_lshlrev_b32_e32 v86, 16, v234
	v_and_b32_e32 v87, 0xffff0000, v234
	v_lshlrev_b32_e32 v70, 16, v235
	v_and_b32_e32 v71, 0xffff0000, v235
	v_pk_fma_f32 v[62:63], v[62:63], v[138:139], v[68:69]
	v_pk_fma_f32 v[60:61], v[60:61], v[136:137], v[82:83]
	v_pk_fma_f32 v[68:69], v[58:59], v[134:135], v[70:71]
	v_pk_fma_f32 v[58:59], v[56:57], v[132:133], v[86:87]
	v_cvt_pk_bf16_f32 v56, v60, v61
	v_cvt_pk_bf16_f32 v57, v62, v63
	s_nop 0
	v_cvt_pk_bf16_f32 v58, v58, v59
	v_cvt_pk_bf16_f32 v59, v68, v69
	v_add_co_u32_e32 v68, vcc, s91, v146
	global_store_dwordx4 v[84:85], v[56:59], off
	s_nop 0
	v_addc_co_u32_e32 v69, vcc, 0, v147, vcc
	s_waitcnt vmcnt(15)
	v_lshlrev_b32_e32 v70, 16, v236
	v_and_b32_e32 v71, 0xffff0000, v236
	v_lshlrev_b32_e32 v60, 16, v237
	v_and_b32_e32 v61, 0xffff0000, v237
	v_lshlrev_b32_e32 v82, 16, v238
	v_and_b32_e32 v83, 0xffff0000, v238
	v_lshlrev_b32_e32 v62, 16, v239
	v_and_b32_e32 v63, 0xffff0000, v239
	v_pk_fma_f32 v[54:55], v[54:55], v[126:127], v[60:61]
	v_pk_fma_f32 v[52:53], v[52:53], v[124:125], v[70:71]
	v_pk_fma_f32 v[60:61], v[46:47], v[122:123], v[62:63]
	v_pk_fma_f32 v[46:47], v[44:45], v[120:121], v[82:83]
	v_cvt_pk_bf16_f32 v44, v52, v53
	v_cvt_pk_bf16_f32 v45, v54, v55
	s_nop 0
	v_cvt_pk_bf16_f32 v46, v46, v47
	v_cvt_pk_bf16_f32 v47, v60, v61
	v_lshl_add_u64 v[60:61], v[146:147], 0, s[4:5]
	global_store_dwordx4 v[80:81], v[44:47], off offset:256
	s_mov_b32 s4, 0xa0000
	s_waitcnt vmcnt(15)
	v_lshlrev_b32_e32 v62, 16, v240
	v_and_b32_e32 v63, 0xffff0000, v240
	v_lshlrev_b32_e32 v52, 16, v241
	v_and_b32_e32 v53, 0xffff0000, v241
	v_lshlrev_b32_e32 v70, 16, v242
	v_and_b32_e32 v71, 0xffff0000, v242
	v_lshlrev_b32_e32 v54, 16, v243
	v_and_b32_e32 v55, 0xffff0000, v243
	v_pk_fma_f32 v[50:51], v[50:51], v[138:139], v[52:53]
	v_pk_fma_f32 v[48:49], v[48:49], v[136:137], v[62:63]
	v_pk_fma_f32 v[52:53], v[42:43], v[134:135], v[54:55]
	v_pk_fma_f32 v[42:43], v[40:41], v[132:133], v[70:71]
	v_cvt_pk_bf16_f32 v40, v48, v49
	v_cvt_pk_bf16_f32 v41, v50, v51
	s_nop 0
	v_cvt_pk_bf16_f32 v42, v42, v43
	v_cvt_pk_bf16_f32 v43, v52, v53
	v_add_co_u32_e32 v52, vcc, s4, v146
	global_store_dwordx4 v[68:69], v[40:43], off
	s_nop 0
	v_addc_co_u32_e32 v53, vcc, 0, v147, vcc
	s_mov_b64 s[4:5], 0xa0000
	s_waitcnt vmcnt(14)
	v_lshlrev_b32_e32 v54, 16, v186
	v_and_b32_e32 v55, 0xffff0000, v186
	v_lshlrev_b32_e32 v48, 16, v187
	v_and_b32_e32 v49, 0xffff0000, v187
	v_lshlrev_b32_e32 v62, 16, v188
	v_and_b32_e32 v63, 0xffff0000, v188
	v_lshlrev_b32_e32 v50, 16, v189
	v_and_b32_e32 v51, 0xffff0000, v189
	v_pk_fma_f32 v[38:39], v[38:39], v[126:127], v[48:49]
	v_pk_fma_f32 v[48:49], v[30:31], v[122:123], v[50:51]
	v_pk_fma_f32 v[30:31], v[28:29], v[120:121], v[62:63]
	v_pk_fma_f32 v[36:37], v[36:37], v[124:125], v[54:55]
	s_nop 0
	v_cvt_pk_bf16_f32 v28, v36, v37
	v_cvt_pk_bf16_f32 v29, v38, v39
	v_cvt_pk_bf16_f32 v30, v30, v31
	v_cvt_pk_bf16_f32 v31, v48, v49
	global_store_dwordx4 v[60:61], v[28:31], off offset:256
	v_lshl_add_u64 v[48:49], v[146:147], 0, s[4:5]
	s_mov_b32 s4, 0xb0000
	s_waitcnt vmcnt(14)
	v_lshlrev_b32_e32 v50, 16, v190
	v_and_b32_e32 v51, 0xffff0000, v190
	v_lshlrev_b32_e32 v36, 16, v191
	v_and_b32_e32 v37, 0xffff0000, v191
	v_lshlrev_b32_e32 v54, 16, v192
	v_and_b32_e32 v55, 0xffff0000, v192
	v_lshlrev_b32_e32 v38, 16, v193
	v_and_b32_e32 v39, 0xffff0000, v193
	v_pk_fma_f32 v[34:35], v[34:35], v[138:139], v[36:37]
	v_pk_fma_f32 v[32:33], v[32:33], v[136:137], v[50:51]
	v_pk_fma_f32 v[36:37], v[26:27], v[134:135], v[38:39]
	v_pk_fma_f32 v[26:27], v[24:25], v[132:133], v[54:55]
	v_cvt_pk_bf16_f32 v24, v32, v33
	v_cvt_pk_bf16_f32 v25, v34, v35
	s_nop 0
	v_cvt_pk_bf16_f32 v26, v26, v27
	v_cvt_pk_bf16_f32 v27, v36, v37
	v_add_co_u32_e32 v36, vcc, s4, v146
	global_store_dwordx4 v[52:53], v[24:27], off
	s_nop 0
	v_addc_co_u32_e32 v37, vcc, 0, v147, vcc
	s_mov_b64 s[4:5], 0xb0000
	s_waitcnt vmcnt(12)
	v_lshlrev_b32_e32 v38, 16, v200
	v_and_b32_e32 v39, 0xffff0000, v200
	v_lshlrev_b32_e32 v32, 16, v201
	v_and_b32_e32 v33, 0xffff0000, v201
	v_lshlrev_b32_e32 v50, 16, v202
	v_and_b32_e32 v51, 0xffff0000, v202
	v_lshlrev_b32_e32 v34, 16, v203
	v_and_b32_e32 v35, 0xffff0000, v203
	v_pk_fma_f32 v[22:23], v[22:23], v[126:127], v[32:33]
	v_pk_fma_f32 v[20:21], v[20:21], v[124:125], v[38:39]
	v_pk_fma_f32 v[32:33], v[14:15], v[122:123], v[34:35]
	v_pk_fma_f32 v[14:15], v[12:13], v[120:121], v[50:51]
	v_cvt_pk_bf16_f32 v12, v20, v21
	v_cvt_pk_bf16_f32 v13, v22, v23
	s_nop 0
	v_cvt_pk_bf16_f32 v14, v14, v15
	v_cvt_pk_bf16_f32 v15, v32, v33
	v_lshl_add_u64 v[32:33], v[146:147], 0, s[4:5]
	global_store_dwordx4 v[48:49], v[12:15], off offset:256
	v_readlane_b32 s4, v255, 5
	v_readlane_b32 s5, v255, 6
	s_andn2_b64 vcc, exec, s[4:5]
	s_waitcnt vmcnt(11)
	v_lshlrev_b32_e32 v34, 16, v204
	v_and_b32_e32 v35, 0xffff0000, v204
	v_lshlrev_b32_e32 v20, 16, v205
	v_and_b32_e32 v21, 0xffff0000, v205
	v_lshlrev_b32_e32 v38, 16, v206
	v_and_b32_e32 v39, 0xffff0000, v206
	v_lshlrev_b32_e32 v22, 16, v207
	v_and_b32_e32 v23, 0xffff0000, v207
	v_pk_fma_f32 v[18:19], v[18:19], v[138:139], v[20:21]
	v_pk_fma_f32 v[16:17], v[16:17], v[136:137], v[34:35]
	v_pk_fma_f32 v[20:21], v[10:11], v[134:135], v[22:23]
	v_pk_fma_f32 v[10:11], v[8:9], v[132:133], v[38:39]
	v_cvt_pk_bf16_f32 v8, v16, v17
	v_cvt_pk_bf16_f32 v9, v18, v19
	s_nop 0
	v_cvt_pk_bf16_f32 v10, v10, v11
	v_cvt_pk_bf16_f32 v11, v20, v21
	s_waitcnt vmcnt(9)
	v_lshlrev_b32_e32 v20, 16, v208
	v_and_b32_e32 v21, 0xffff0000, v208
	v_lshlrev_b32_e32 v16, 16, v209
	v_and_b32_e32 v17, 0xffff0000, v209
	v_lshlrev_b32_e32 v22, 16, v210
	v_and_b32_e32 v23, 0xffff0000, v210
	v_lshlrev_b32_e32 v18, 16, v211
	v_and_b32_e32 v19, 0xffff0000, v211
	v_pk_fma_f32 v[6:7], v[6:7], v[126:127], v[16:17]
	v_pk_fma_f32 v[16:17], v[2:3], v[122:123], v[18:19]
	v_pk_fma_f32 v[2:3], v[0:1], v[120:121], v[22:23]
	global_store_dwordx4 v[36:37], v[8:11], off
	v_pk_fma_f32 v[4:5], v[4:5], v[124:125], v[20:21]
	s_nop 0
	v_cvt_pk_bf16_f32 v0, v4, v5
	v_cvt_pk_bf16_f32 v1, v6, v7
	v_cvt_pk_bf16_f32 v2, v2, v3
	v_cvt_pk_bf16_f32 v3, v16, v17
	global_store_dwordx4 v[32:33], v[0:3], off offset:256
	s_cbranch_vccnz .LBB0_1542
	v_and_b32_e32 v35, 0xffff0000, v128
	v_and_b32_e32 v33, 0xffff0000, v129
	v_lshlrev_b32_e32 v34, 16, v128
	v_lshlrev_b32_e32 v32, 16, v129
	v_mul_f32_e32 v4, v35, v35
	v_mul_f32_e32 v5, v33, v33
	v_and_b32_e32 v39, 0xffff0000, v130
	v_fmac_f32_e32 v4, v34, v34
	v_fmac_f32_e32 v5, v32, v32
	v_lshlrev_b32_e32 v38, 16, v130
	v_add_f32_e32 v4, v4, v5
	v_mul_f32_e32 v5, v39, v39
	v_and_b32_e32 v37, 0xffff0000, v131
	v_fmac_f32_e32 v5, v38, v38
	v_lshlrev_b32_e32 v36, 16, v131
	v_add_f32_e32 v4, v4, v5
	v_mul_f32_e32 v5, v37, v37
	v_and_b32_e32 v159, 0xffff0000, v108
	v_and_b32_e32 v161, 0xffff0000, v109
	v_fmac_f32_e32 v5, v36, v36
	v_lshlrev_b32_e32 v158, 16, v108
	v_lshlrev_b32_e32 v160, 16, v109
	v_add_f32_e32 v4, v4, v5
	v_mul_f32_e32 v5, v159, v159
	v_mul_f32_e32 v6, v161, v161
	v_and_b32_e32 v155, 0xffff0000, v110
	v_fmac_f32_e32 v5, v158, v158
	v_fmac_f32_e32 v6, v160, v160
	v_lshlrev_b32_e32 v154, 16, v110
	v_add_f32_e32 v5, v5, v6
	v_mul_f32_e32 v6, v155, v155
	v_and_b32_e32 v157, 0xffff0000, v111
	v_fmac_f32_e32 v6, v154, v154
	v_lshlrev_b32_e32 v156, 16, v111
	v_add_f32_e32 v5, v5, v6
	v_mul_f32_e32 v6, v157, v157
	v_fmac_f32_e32 v6, v156, v156
	v_add_f32_e32 v5, v5, v6
	v_lshlrev_b32_e32 v6, 2, v162
	v_add_f32_e32 v4, v4, v5
	v_xor_b32_e32 v5, 64, v6
	ds_bpermute_b32 v7, v5, v4
	v_xor_b32_e32 v6, 0x80, v6
	v_readlane_b32 s4, v254, 29
	v_cmp_gt_u32_e32 vcc, 16, v162
	s_waitcnt lgkmcnt(0)
	v_add_f32_e32 v7, v4, v7
	ds_bpermute_b32 v16, v6, v7
	v_lshl_add_u32 v4, v162, 4, s4
	s_and_saveexec_b64 s[4:5], vcc
	s_cbranch_execz .LBB0_1431
	s_waitcnt lgkmcnt(0)
	v_add_f32_e32 v7, v7, v16
	ds_write_b32 v4, v7
